# flash B loop (MLA, d=96) softmax/PV hand-scheduled like the A loop
# speedup vs baseline: 1.0520x; 1.0051x over previous
.LBB0_581:
	s_mul_i32 s8, s7, 0x5000
	s_add_i32 s8, s8, 0
	v_add_u32_e32 v3, s8, v142
	ds_read_b128 v[60:63], v3
	ds_read_b128 v[64:67], v3 offset:64
	ds_read_b128 v[68:71], v3 offset:128
	ds_read_b128 v[72:75], v3 offset:3072
	ds_read_b128 v[76:79], v3 offset:3136
	ds_read_b128 v[80:83], v3 offset:3200
	ds_read_b128 v[84:87], v3 offset:6144
	ds_read_b128 v[88:91], v3 offset:6208
	ds_read_b128 v[92:95], v3 offset:6272
	ds_read_b128 v[96:99], v3 offset:9216
	ds_read_b128 v[108:111], v3 offset:9280
	ds_read_b128 v[146:149], v3 offset:9344
	s_waitcnt lgkmcnt(0)
	v_mfma_f32_16x16x32_bf16 v[100:103], v[60:63], v[8:11], 0
	v_add_u32_e32 v3, s8, v141
	v_mfma_f32_16x16x32_bf16 v[60:63], v[60:63], v[44:47], 0
	v_mfma_f32_16x16x32_bf16 v[60:63], v[64:67], v[32:35], v[60:63]
	v_mfma_f32_16x16x32_bf16 v[100:103], v[64:67], v[4:7], v[100:103]
	v_mfma_f32_16x16x32_bf16 v[104:107], v[68:71], v[56:59], v[60:63]
	v_mfma_f32_16x16x32_bf16 v[60:63], v[72:75], v[8:11], 0
	v_mfma_f32_16x16x32_bf16 v[64:67], v[72:75], v[44:47], 0
	v_mfma_f32_16x16x32_bf16 v[60:63], v[76:79], v[4:7], v[60:63]
	v_mfma_f32_16x16x32_bf16 v[64:67], v[76:79], v[32:35], v[64:67]
	v_mfma_f32_16x16x32_bf16 v[120:123], v[68:71], v[12:15], v[100:103]
	v_mfma_f32_16x16x32_bf16 v[116:119], v[80:83], v[12:15], v[60:63]
	v_mfma_f32_16x16x32_bf16 v[100:103], v[80:83], v[56:59], v[64:67]
	v_mfma_f32_16x16x32_bf16 v[60:63], v[84:87], v[8:11], 0
	v_mfma_f32_16x16x32_bf16 v[64:67], v[84:87], v[44:47], 0
	v_mfma_f32_16x16x32_bf16 v[60:63], v[88:91], v[4:7], v[60:63]
	v_mfma_f32_16x16x32_bf16 v[64:67], v[88:91], v[32:35], v[64:67]
	v_mfma_f32_16x16x32_bf16 v[112:115], v[92:95], v[12:15], v[60:63]
	v_mfma_f32_16x16x32_bf16 v[72:75], v[92:95], v[56:59], v[64:67]
	v_mfma_f32_16x16x32_bf16 v[60:63], v[96:99], v[8:11], 0
	v_mfma_f32_16x16x32_bf16 v[64:67], v[96:99], v[44:47], 0
	v_mfma_f32_16x16x32_bf16 v[60:63], v[108:111], v[4:7], v[60:63]
	v_mfma_f32_16x16x32_bf16 v[64:67], v[108:111], v[32:35], v[64:67]
	v_mfma_f32_16x16x32_bf16 v[108:111], v[146:149], v[12:15], v[60:63]
	v_mfma_f32_16x16x32_bf16 v[60:63], v[146:149], v[56:59], v[64:67]
	s_nop 5
	v_add_u32_e32 v3, s8, v141
	v_add_u32_e32 v146, s8, v140
	ds_read_b64 v[96:97], v3 offset:12288
	ds_read_b64 v[98:99], v146 offset:12288
	ds_read_b64 v[92:93], v3 offset:14336
	ds_read_b64 v[94:95], v146 offset:14336
	ds_read_b64 v[88:89], v3 offset:16384
	ds_read_b64 v[90:91], v146 offset:16384
	ds_read_b64 v[84:85], v3 offset:18432
	ds_read_b64 v[86:87], v146 offset:18432
	v_add_u32_e32 v3, s8, v139
	v_add_u32_e32 v146, s8, v138
	ds_read_b64 v[80:81], v3 offset:12288
	ds_read_b64 v[82:83], v146 offset:12288
	ds_read_b64 v[76:77], v3 offset:14336
	ds_read_b64 v[78:79], v146 offset:14336
	ds_read_b64 v[68:69], v3 offset:16384
	ds_read_b64 v[70:71], v146 offset:16384
	ds_read_b64 v[64:65], v3 offset:18432
	ds_read_b64 v[66:67], v146 offset:18432
	v_max3_f32 v143, v120, v121, v122
	v_max3_f32 v144, v104, v105, v106
	v_max3_f32 v143, v143, v123, v116
	v_max3_f32 v144, v144, v107, v100
	v_max3_f32 v143, v143, v117, v118
	v_max3_f32 v144, v144, v101, v102
	v_max3_f32 v143, v143, v119, v112
	v_max3_f32 v144, v144, v103, v72
	v_max3_f32 v143, v143, v113, v114
	v_max3_f32 v144, v144, v73, v74
	v_max3_f32 v143, v143, v115, v108
	v_max3_f32 v144, v144, v75, v60
	v_max3_f32 v143, v143, v109, v110
	v_max3_f32 v144, v144, v61, v62
	v_max_f32_e32 v143, v143, v111
	v_max_f32_e32 v144, v144, v63
	v_mov_b32_e32 v3, v143
	v_mov_b32_e32 v146, v144
	s_nop 0
	v_permlane16_swap_b32_e32 v143, v3
	v_permlane16_swap_b32_e32 v144, v146
	v_max_f32_e32 v143, v143, v3
	v_max_f32_e32 v144, v144, v146
	v_mov_b32_e32 v3, v143
	v_mov_b32_e32 v146, v144
	s_nop 0
	v_permlane32_swap_b32_e32 v143, v3
	v_permlane32_swap_b32_e32 v144, v146
	v_max_f32_e32 v143, v143, v3
	v_max_f32_e32 v144, v144, v146
	v_mul_f32_e32 v143, s23, v143
	v_mul_f32_e32 v144, s23, v144
	v_max_f32_e32 v143, v2, v143
	v_max_f32_e32 v144, v145, v144
	v_cmp_gt_f32_e32 vcc, v143, v2
	s_cbranch_vccnz .Lfa_b_rescale
	v_cmp_gt_f32_e32 vcc, v144, v145
	s_cbranch_vccz .Lfa_b_norescale
.Lfa_b_rescale:
	v_sub_f32_e32 v148, v2, v143
	v_exp_f32_e32 v148, v148
	v_sub_f32_e32 v3, v145, v144
	v_exp_f32_e32 v3, v3
	v_mul_f32_e32 v1, v1, v148
	v_pk_mul_f32 v[52:53], v[52:53], v[148:149] op_sel_hi:[1,0]
	v_pk_mul_f32 v[54:55], v[54:55], v[148:149] op_sel_hi:[1,0]
	v_pk_mul_f32 v[40:41], v[40:41], v[148:149] op_sel_hi:[1,0]
	v_pk_mul_f32 v[42:43], v[42:43], v[148:149] op_sel_hi:[1,0]
	v_pk_mul_f32 v[28:29], v[28:29], v[148:149] op_sel_hi:[1,0]
	v_pk_mul_f32 v[30:31], v[30:31], v[148:149] op_sel_hi:[1,0]
	v_pk_mul_f32 v[20:21], v[20:21], v[148:149] op_sel_hi:[1,0]
	v_pk_mul_f32 v[22:23], v[22:23], v[148:149] op_sel_hi:[1,0]
	v_mov_b32_e32 v148, v3
	v_mul_f32_e32 v137, v137, v3
	v_pk_mul_f32 v[48:49], v[48:49], v[148:149] op_sel_hi:[1,0]
	v_pk_mul_f32 v[50:51], v[50:51], v[148:149] op_sel_hi:[1,0]
	v_pk_mul_f32 v[36:37], v[36:37], v[148:149] op_sel_hi:[1,0]
	v_pk_mul_f32 v[38:39], v[38:39], v[148:149] op_sel_hi:[1,0]
	v_pk_mul_f32 v[24:25], v[24:25], v[148:149] op_sel_hi:[1,0]
	v_pk_mul_f32 v[26:27], v[26:27], v[148:149] op_sel_hi:[1,0]
	v_pk_mul_f32 v[16:17], v[16:17], v[148:149] op_sel_hi:[1,0]
	v_pk_mul_f32 v[18:19], v[18:19], v[148:149] op_sel_hi:[1,0]
.Lfa_b_norescale:
	v_fma_f32 v120, v120, s23, -v143
	v_exp_f32_e32 v120, v120
	v_fma_f32 v104, v104, s23, -v144
	v_exp_f32_e32 v104, v104
	v_fma_f32 v121, v121, s23, -v143
	v_exp_f32_e32 v121, v121
	v_fma_f32 v105, v105, s23, -v144
	v_exp_f32_e32 v105, v105
	v_fma_f32 v122, v122, s23, -v143
	v_exp_f32_e32 v122, v122
	v_fma_f32 v106, v106, s23, -v144
	v_exp_f32_e32 v106, v106
	v_fma_f32 v123, v123, s23, -v143
	v_exp_f32_e32 v123, v123
	v_fma_f32 v107, v107, s23, -v144
	v_exp_f32_e32 v107, v107
	v_fma_f32 v116, v116, s23, -v143
	v_exp_f32_e32 v116, v116
	v_fma_f32 v100, v100, s23, -v144
	v_exp_f32_e32 v100, v100
	v_fma_f32 v117, v117, s23, -v143
	v_exp_f32_e32 v117, v117
	v_fma_f32 v101, v101, s23, -v144
	v_exp_f32_e32 v101, v101
	v_fma_f32 v118, v118, s23, -v143
	v_exp_f32_e32 v118, v118
	v_fma_f32 v102, v102, s23, -v144
	v_exp_f32_e32 v102, v102
	v_fma_f32 v119, v119, s23, -v143
	v_exp_f32_e32 v119, v119
	v_fma_f32 v103, v103, s23, -v144
	v_exp_f32_e32 v103, v103
	v_pk_add_f32 v[148:149], v[120:121], v[122:123]
	v_pk_add_f32 v[148:149], v[148:149], v[116:117]
	v_pk_add_f32 v[148:149], v[148:149], v[118:119]
	v_add_f32_e32 v148, v148, v149
	v_add_f32_e32 v1, v1, v148
	v_pk_add_f32 v[148:149], v[104:105], v[106:107]
	v_pk_add_f32 v[148:149], v[148:149], v[100:101]
	v_pk_add_f32 v[148:149], v[148:149], v[102:103]
	v_add_f32_e32 v148, v148, v149
	v_add_f32_e32 v137, v137, v148
	v_cvt_pk_bf16_f32 v120, v120, v121
	v_cvt_pk_bf16_f32 v121, v122, v123
	v_cvt_pk_bf16_f32 v122, v116, v117
	v_cvt_pk_bf16_f32 v123, v118, v119
	v_cvt_pk_bf16_f32 v104, v104, v105
	v_cvt_pk_bf16_f32 v105, v106, v107
	v_cvt_pk_bf16_f32 v106, v100, v101
	v_cvt_pk_bf16_f32 v107, v102, v103
	s_waitcnt lgkmcnt(0)
	s_add_i32 s7, s7, 1
	s_cmp_lg_u32 s7, 3
	s_cselect_b32 s7, s7, 0
	v_mfma_f32_16x16x32_bf16 v[52:55], v[96:99], v[120:123], v[52:55]
	v_fma_f32 v112, v112, s23, -v143
	v_exp_f32_e32 v112, v112
	v_fma_f32 v72, v72, s23, -v144
	v_exp_f32_e32 v72, v72
	v_mfma_f32_16x16x32_bf16 v[48:51], v[96:99], v[104:107], v[48:51]
	v_fma_f32 v113, v113, s23, -v143
	v_exp_f32_e32 v113, v113
	v_fma_f32 v73, v73, s23, -v144
	v_exp_f32_e32 v73, v73
	v_mfma_f32_16x16x32_bf16 v[40:43], v[92:95], v[120:123], v[40:43]
	v_fma_f32 v114, v114, s23, -v143
	v_exp_f32_e32 v114, v114
	v_fma_f32 v74, v74, s23, -v144
	v_exp_f32_e32 v74, v74
	v_mfma_f32_16x16x32_bf16 v[36:39], v[92:95], v[104:107], v[36:39]
	v_fma_f32 v115, v115, s23, -v143
	v_exp_f32_e32 v115, v115
	v_fma_f32 v75, v75, s23, -v144
	v_exp_f32_e32 v75, v75
	v_mfma_f32_16x16x32_bf16 v[28:31], v[88:91], v[120:123], v[28:31]
	v_fma_f32 v108, v108, s23, -v143
	v_exp_f32_e32 v108, v108
	v_fma_f32 v60, v60, s23, -v144
	v_exp_f32_e32 v60, v60
	v_mfma_f32_16x16x32_bf16 v[24:27], v[88:91], v[104:107], v[24:27]
	v_fma_f32 v109, v109, s23, -v143
	v_exp_f32_e32 v109, v109
	v_fma_f32 v61, v61, s23, -v144
	v_exp_f32_e32 v61, v61
	v_mfma_f32_16x16x32_bf16 v[20:23], v[84:87], v[120:123], v[20:23]
	v_fma_f32 v110, v110, s23, -v143
	v_exp_f32_e32 v110, v110
	v_fma_f32 v62, v62, s23, -v144
	v_exp_f32_e32 v62, v62
	v_mfma_f32_16x16x32_bf16 v[16:19], v[84:87], v[104:107], v[16:19]
	v_fma_f32 v111, v111, s23, -v143
	v_exp_f32_e32 v111, v111
	v_fma_f32 v63, v63, s23, -v144
	v_exp_f32_e32 v63, v63
	v_pk_add_f32 v[148:149], v[112:113], v[114:115]
	v_pk_add_f32 v[148:149], v[148:149], v[108:109]
	v_pk_add_f32 v[148:149], v[148:149], v[110:111]
	v_add_f32_e32 v148, v148, v149
	v_add_f32_e32 v1, v1, v148
	v_pk_add_f32 v[148:149], v[72:73], v[74:75]
	v_pk_add_f32 v[148:149], v[148:149], v[60:61]
	v_pk_add_f32 v[148:149], v[148:149], v[62:63]
	v_add_f32_e32 v148, v148, v149
	v_add_f32_e32 v137, v137, v148
	v_cvt_pk_bf16_f32 v112, v112, v113
	v_cvt_pk_bf16_f32 v113, v114, v115
	v_cvt_pk_bf16_f32 v114, v108, v109
	v_cvt_pk_bf16_f32 v115, v110, v111
	v_cvt_pk_bf16_f32 v72, v72, v73
	v_cvt_pk_bf16_f32 v73, v74, v75
	v_cvt_pk_bf16_f32 v74, v60, v61
	v_cvt_pk_bf16_f32 v75, v62, v63
	v_lshl_add_u64 v[124:125], v[124:125], 0, s[24:25]
	v_lshl_add_u64 v[126:127], v[126:127], 0, s[24:25]
	v_lshl_add_u64 v[128:129], v[128:129], 0, s[90:91]
	v_lshl_add_u64 v[130:131], v[130:131], 0, s[90:91]
	v_lshl_add_u64 v[132:133], v[132:133], 0, s[90:91]
	v_mfma_f32_16x16x32_bf16 v[52:55], v[80:83], v[112:115], v[52:55]
	v_mfma_f32_16x16x32_bf16 v[48:51], v[80:83], v[72:75], v[48:51]
	v_mfma_f32_16x16x32_bf16 v[40:43], v[76:79], v[112:115], v[40:43]
	v_mfma_f32_16x16x32_bf16 v[36:39], v[76:79], v[72:75], v[36:39]
	v_mfma_f32_16x16x32_bf16 v[28:31], v[68:71], v[112:115], v[28:31]
	v_mfma_f32_16x16x32_bf16 v[24:27], v[68:71], v[72:75], v[24:27]
	v_mfma_f32_16x16x32_bf16 v[20:23], v[64:67], v[112:115], v[20:23]
	v_mfma_f32_16x16x32_bf16 v[16:19], v[64:67], v[72:75], v[16:19]
	s_cmp_eq_u32 s58, s6
	s_cbranch_scc1 .LBB0_587
	v_mov_b32_e32 v145, v144
	v_mov_b32_e32 v2, v143
	s_branch .LBB0_579
